# hyena filter L1-norm sum loop: 3 iterations of loads in flight with counted waits (same summation order)
# speedup vs baseline: 1.0178x; 1.0016x over previous
; __global__ void __launch_bounds__(NTHR, 2) fwd_mega(Args a) {
;     ...
;                     float s = 0.f; for (int i = tid; i < 8192; i += NTHR) s += fabsf(hf[i]) + fabsf(hb[i]);
.LBB0_511:
	global_load_dword v9, v[6:7], off
	global_load_dword v10, v[4:5], off
	v_lshl_add_u64 v[4:5], v[4:5], 0, s[16:17]
	v_lshl_add_u64 v[6:7], v[6:7], 0, s[16:17]
	global_load_dword v11, v[6:7], off
	global_load_dword v12, v[4:5], off
	v_lshl_add_u64 v[4:5], v[4:5], 0, s[16:17]
	v_lshl_add_u64 v[6:7], v[6:7], 0, s[16:17]
	global_load_dword v13, v[6:7], off
	global_load_dword v14, v[4:5], off
	v_lshl_add_u64 v[4:5], v[4:5], 0, s[16:17]
	v_lshl_add_u64 v[6:7], v[6:7], 0, s[16:17]
	s_waitcnt vmcnt(4) lgkmcnt(0)
	v_add_f32_e64 v9, |v9|, |v10|
	v_add_f32_e32 v1, v1, v9
	s_waitcnt vmcnt(2)
	v_add_f32_e64 v11, |v11|, |v12|
	v_add_f32_e32 v1, v1, v11
	s_waitcnt vmcnt(0)
	v_add_f32_e64 v13, |v13|, |v14|
	v_add_f32_e32 v1, v1, v13
	global_load_dword v9, v[6:7], off
	global_load_dword v10, v[4:5], off
	v_lshl_add_u64 v[4:5], v[4:5], 0, s[16:17]
	v_lshl_add_u64 v[6:7], v[6:7], 0, s[16:17]
	global_load_dword v11, v[6:7], off
	global_load_dword v12, v[4:5], off
	v_lshl_add_u64 v[4:5], v[4:5], 0, s[16:17]
	v_lshl_add_u64 v[6:7], v[6:7], 0, s[16:17]
	global_load_dword v13, v[6:7], off
	global_load_dword v14, v[4:5], off
	v_lshl_add_u64 v[4:5], v[4:5], 0, s[16:17]
	v_lshl_add_u64 v[6:7], v[6:7], 0, s[16:17]
	s_waitcnt vmcnt(4)
	v_add_f32_e64 v9, |v9|, |v10|
	v_add_f32_e32 v1, v1, v9
	s_waitcnt vmcnt(2)
	v_add_f32_e64 v11, |v11|, |v12|
	v_add_f32_e32 v1, v1, v11
	s_waitcnt vmcnt(0)
	v_add_f32_e64 v13, |v13|, |v14|
	v_add_f32_e32 v1, v1, v13
	global_load_dword v9, v[6:7], off
	global_load_dword v10, v[4:5], off
	v_lshl_add_u64 v[4:5], v[4:5], 0, s[16:17]
	v_lshl_add_u64 v[6:7], v[6:7], 0, s[16:17]
	global_load_dword v11, v[6:7], off
	global_load_dword v12, v[4:5], off
	v_lshl_add_u64 v[4:5], v[4:5], 0, s[16:17]
	v_lshl_add_u64 v[6:7], v[6:7], 0, s[16:17]
	global_load_dword v13, v[6:7], off
	global_load_dword v14, v[4:5], off
	v_lshl_add_u64 v[4:5], v[4:5], 0, s[16:17]
	v_lshl_add_u64 v[6:7], v[6:7], 0, s[16:17]
	s_waitcnt vmcnt(4)
	v_add_f32_e64 v9, |v9|, |v10|
	v_add_f32_e32 v1, v1, v9
	s_waitcnt vmcnt(2)
	v_add_f32_e64 v11, |v11|, |v12|
	v_add_f32_e32 v1, v1, v11
	s_waitcnt vmcnt(0)
	v_add_f32_e64 v13, |v13|, |v14|
	v_add_f32_e32 v1, v1, v13
	global_load_dword v9, v[6:7], off
	global_load_dword v10, v[4:5], off
	v_lshl_add_u64 v[4:5], v[4:5], 0, s[16:17]
	v_lshl_add_u64 v[6:7], v[6:7], 0, s[16:17]
	global_load_dword v11, v[6:7], off
	global_load_dword v12, v[4:5], off
	v_lshl_add_u64 v[4:5], v[4:5], 0, s[16:17]
	v_lshl_add_u64 v[6:7], v[6:7], 0, s[16:17]
	global_load_dword v13, v[6:7], off
	global_load_dword v14, v[4:5], off
	v_lshl_add_u64 v[4:5], v[4:5], 0, s[16:17]
	v_lshl_add_u64 v[6:7], v[6:7], 0, s[16:17]
	s_waitcnt vmcnt(4)
	v_add_f32_e64 v9, |v9|, |v10|
	v_add_f32_e32 v1, v1, v9
	s_waitcnt vmcnt(2)
	v_add_f32_e64 v11, |v11|, |v12|
	v_add_f32_e32 v1, v1, v11
	s_waitcnt vmcnt(0)
	v_add_f32_e64 v13, |v13|, |v14|
	v_add_f32_e32 v1, v1, v13
	global_load_dword v9, v[6:7], off
	global_load_dword v10, v[4:5], off
	v_lshl_add_u64 v[4:5], v[4:5], 0, s[16:17]
	v_lshl_add_u64 v[6:7], v[6:7], 0, s[16:17]
	global_load_dword v11, v[6:7], off
	global_load_dword v12, v[4:5], off
	v_lshl_add_u64 v[4:5], v[4:5], 0, s[16:17]
	v_lshl_add_u64 v[6:7], v[6:7], 0, s[16:17]
	global_load_dword v13, v[6:7], off
	global_load_dword v14, v[4:5], off
	v_lshl_add_u64 v[4:5], v[4:5], 0, s[16:17]
	v_lshl_add_u64 v[6:7], v[6:7], 0, s[16:17]
	s_waitcnt vmcnt(4)
	v_add_f32_e64 v9, |v9|, |v10|
	v_add_f32_e32 v1, v1, v9
	s_waitcnt vmcnt(2)
	v_add_f32_e64 v11, |v11|, |v12|
	v_add_f32_e32 v1, v1, v11
	s_waitcnt vmcnt(0)
	v_add_f32_e64 v13, |v13|, |v14|
	v_add_f32_e32 v1, v1, v13
	global_load_dword v9, v[6:7], off
	global_load_dword v10, v[4:5], off
	v_lshl_add_u64 v[4:5], v[4:5], 0, s[16:17]
	v_lshl_add_u64 v[6:7], v[6:7], 0, s[16:17]
	s_waitcnt vmcnt(0)
	v_add_f32_e64 v9, |v9|, |v10|
	v_add_f32_e32 v1, v1, v9
	s_or_b64 exec, exec, s[10:11]
